# leader pre-advances its clock by 6 units across its sweep boundary
# speedup vs baseline: 1.0151x; 1.0151x over previous
.Lxp_noswe:
	s_mov_b32 s80, s81
	s_mov_b32 s81, s94
	s_add_i32 s25, s25, 1
	s_cmp_eq_u32 s82, 1
	s_cbranch_scc0 .Lxp_nojump
	s_add_i32 s2, s97, 17024
	s_and_b32 s2, s2, 0x3fff
	v_mov_b32_e32 v245, s2
	s_mov_b64 exec, 1
	global_store_dword v[246:247], v245, off
	s_mov_b64 exec, -1
